# e31+e29 with no 64B-straddling wide instructions in the A-loop as well (8 nops)
# baseline (speedup 1.0000x reference)
; __device__ __forceinline__ int crow(int r, int hi) { return (r & 3) + 8 * (r >> 2) + 4 * hi; }
; __device__ __forceinline__ int crow(int r, int hi) { return (r & 3) + 8 * (r >> 2) + 4 * hi; }
; __device__ __forceinline__ void qkt(f32x16& p0, f32x16& p1, const char* Ks, const bf16x8* qr, int r32, int hi) {
;   p0 = f32x16{}; p1 = f32x16{};
; #pragma unroll
;   for (int d0 = 0; d0 < 8; ++d0) { int cb = (d0 * 16 + hi * 8) * 2;
;     bf16x8 b0 = *reinterpret_cast<const bf16x8*>(Ks + KSWZ(r32, cb));
;     bf16x8 b1 = *reinterpret_cast<const bf16x8*>(Ks + KSWZ(32 + r32, cb));
;     p0 = __builtin_amdgcn_mfma_f32_32x32x16_bf16(b0, qr[d0], p0, 0, 0, 0);
;     p1 = __builtin_amdgcn_mfma_f32_32x32x16_bf16(b1, qr[d0], p1, 0, 0, 0); }
; }
; __device__ __forceinline__ void fix_prompt(f32x16& p0, f32x16& p1, int jt, int lim, int qrow0, int r32, int hi, const float* lut) {
;   if (jt > lim) {
; #pragma unroll
;     for (int r = 0; r < 16; ++r) { p0[r] = -1e30f; p1[r] = -1e30f; }
;   } else if (64 * jt >= qrow0 - 153) {
;     const float* lp = lut + (64 * jt - (qrow0 + r32) + 192);
; #pragma unroll
;     for (int r = 0; r < 16; ++r) { p0[r] += lp[crow(r, hi)]; p1[r] += lp[32 + crow(r, hi)]; }
;   }
.LBB0_447:
	s_setprio 0
	s_and_b32 s14, s10, 1
	s_lshl_b32 s15, s14, 14
	s_add_i32 s23, s15, 0
	s_nop 0
	v_add3_u32 v81, s23, v70, v69
	ds_read_b128 v[82:85], v81
	ds_read_b128 v[208:211], v81 offset:8192
	v_add3_u32 v81, s23, v71, v69
	ds_read_b128 v[212:215], v81
	ds_read_b128 v[216:219], v81 offset:8192
	v_add3_u32 v81, s23, v72, v69
	ds_read_b128 v[220:223], v81
	ds_read_b128 v[224:227], v81 offset:8192
	v_add3_u32 v81, s23, v73, v69
	ds_read_b128 v[228:231], v81
	ds_read_b128 v[232:235], v81 offset:8192
	v_add3_u32 v81, s23, v74, v69
	ds_read_b128 v[236:239], v81
	ds_read_b128 v[240:243], v81 offset:8192
	v_add3_u32 v81, s23, v75, v69
	ds_read_b128 v[244:247], v81
	ds_read_b128 v[248:251], v81 offset:8192
	s_cmp_gt_u32 s10, s5
	s_waitcnt vmcnt(7) lgkmcnt(11)
	v_mfma_f32_32x32x16_bf16 v[4:19], v[82:85], v[36:39], 0
	s_waitcnt lgkmcnt(10)
	v_mfma_f32_32x32x16_bf16 v[20:35], v[208:211], v[36:39], 0
	v_add3_u32 v81, s23, v76, v69
	ds_read_b128 v[132:135], v81
	s_nop 0
	ds_read_b128 v[136:139], v81 offset:8192
	s_waitcnt vmcnt(6) lgkmcnt(11)
	v_mfma_f32_32x32x16_bf16 v[4:19], v[212:215], v[40:43], v[4:19]
	s_waitcnt lgkmcnt(10)
	v_mfma_f32_32x32x16_bf16 v[20:35], v[216:219], v[40:43], v[20:35]
	v_add3_u32 v81, s23, v77, v69
	ds_read_b128 v[140:143], v81
	ds_read_b128 v[144:147], v81 offset:8192
	s_waitcnt vmcnt(5) lgkmcnt(11)
	s_nop 0
	v_mfma_f32_32x32x16_bf16 v[4:19], v[220:223], v[44:47], v[4:19]
	s_waitcnt lgkmcnt(10)
	v_mfma_f32_32x32x16_bf16 v[20:35], v[224:227], v[44:47], v[20:35]
	s_waitcnt vmcnt(4) lgkmcnt(9)
	v_mfma_f32_32x32x16_bf16 v[4:19], v[228:231], v[48:51], v[4:19]
	s_waitcnt lgkmcnt(8)
	v_mfma_f32_32x32x16_bf16 v[20:35], v[232:235], v[48:51], v[20:35]
	s_waitcnt vmcnt(3) lgkmcnt(7)
	v_mfma_f32_32x32x16_bf16 v[4:19], v[236:239], v[52:55], v[4:19]
	s_waitcnt lgkmcnt(6)
	s_nop 0
	v_mfma_f32_32x32x16_bf16 v[20:35], v[240:243], v[52:55], v[20:35]
	s_waitcnt vmcnt(2) lgkmcnt(5)
	v_mfma_f32_32x32x16_bf16 v[4:19], v[244:247], v[56:59], v[4:19]
	s_waitcnt lgkmcnt(4)
	v_mfma_f32_32x32x16_bf16 v[20:35], v[248:251], v[56:59], v[20:35]
	s_waitcnt vmcnt(1) lgkmcnt(3)
	v_mfma_f32_32x32x16_bf16 v[4:19], v[132:135], v[60:63], v[4:19]
	s_waitcnt lgkmcnt(2)
	v_mfma_f32_32x32x16_bf16 v[20:35], v[136:139], v[60:63], v[20:35]
	s_waitcnt vmcnt(0) lgkmcnt(1)
	s_nop 0
	v_mfma_f32_32x32x16_bf16 v[4:19], v[140:143], v[64:67], v[4:19]
	s_waitcnt lgkmcnt(0)
	v_mfma_f32_32x32x16_bf16 v[20:35], v[144:147], v[64:67], v[20:35]
	s_cbranch_scc1 .LBB0_450
	s_cmp_lt_i32 s9, s6
	s_cbranch_scc1 .LBB0_451
	v_add_u32_e32 v81, s8, v78
	v_add_u32_e32 v82, 0x20500, v81
	v_add_u32_e32 v84, 0x20580, v81
	ds_read2_b32 v[82:83], v82 offset1:1
	s_nop 0
	ds_read2_b32 v[84:85], v84 offset1:1
	v_add_u32_e32 v86, 0x20588, v81
	v_add_u32_e32 v88, 0x205a0, v81
	v_add_u32_e32 v90, 0x205a8, v81
	v_add_u32_e32 v92, 0x205c0, v81
	s_waitcnt lgkmcnt(0)
	v_pk_add_f32 v[20:21], v[20:21], v[84:85]
	v_add_u32_e32 v84, 0x20508, v81
	s_nop 0
	ds_read2_b32 v[84:85], v84 offset1:1
	ds_read2_b32 v[86:87], v86 offset1:1
	v_add_u32_e32 v94, 0x205c8, v81
	v_add_u32_e32 v96, 0x205e0, v81
	v_add_u32_e32 v98, 0x20568, v81
	s_waitcnt lgkmcnt(1)
	v_pk_add_f32 v[6:7], v[6:7], v[84:85]
	s_waitcnt lgkmcnt(0)
	v_pk_add_f32 v[22:23], v[22:23], v[86:87]
	v_add_u32_e32 v86, 0x20520, v81
	ds_read2_b32 v[86:87], v86 offset1:1
	ds_read2_b32 v[88:89], v88 offset1:1
	v_pk_add_f32 v[4:5], v[4:5], v[82:83]
	s_waitcnt lgkmcnt(1)
	v_pk_add_f32 v[8:9], v[8:9], v[86:87]
	s_waitcnt lgkmcnt(0)
	v_pk_add_f32 v[24:25], v[24:25], v[88:89]
	v_add_u32_e32 v88, 0x20528, v81
	ds_read2_b32 v[88:89], v88 offset1:1
	ds_read2_b32 v[90:91], v90 offset1:1
	s_waitcnt lgkmcnt(1)
	v_pk_add_f32 v[10:11], v[10:11], v[88:89]
	s_waitcnt lgkmcnt(0)
	v_pk_add_f32 v[26:27], v[26:27], v[90:91]
	v_add_u32_e32 v90, 0x20540, v81
	ds_read2_b32 v[90:91], v90 offset1:1
	ds_read2_b32 v[92:93], v92 offset1:1
	s_waitcnt lgkmcnt(1)
	v_pk_add_f32 v[12:13], v[12:13], v[90:91]
	s_waitcnt lgkmcnt(0)
	v_pk_add_f32 v[28:29], v[28:29], v[92:93]
	v_add_u32_e32 v92, 0x20548, v81
	ds_read2_b32 v[92:93], v92 offset1:1
	ds_read2_b32 v[94:95], v94 offset1:1
	s_waitcnt lgkmcnt(1)
	v_pk_add_f32 v[14:15], v[14:15], v[92:93]
	s_waitcnt lgkmcnt(0)
	v_pk_add_f32 v[30:31], v[30:31], v[94:95]
	v_add_u32_e32 v94, 0x20560, v81
	ds_read2_b32 v[94:95], v94 offset1:1
	ds_read2_b32 v[96:97], v96 offset1:1
	v_add_u32_e32 v81, 0x205e8, v81
	ds_read2_b32 v[98:99], v98 offset1:1
	s_waitcnt lgkmcnt(2)
	v_pk_add_f32 v[16:17], v[16:17], v[94:95]
	s_waitcnt lgkmcnt(1)
	v_pk_add_f32 v[32:33], v[32:33], v[96:97]
	ds_read2_b32 v[96:97], v81 offset1:1
	s_waitcnt lgkmcnt(1)
	v_pk_add_f32 v[18:19], v[18:19], v[98:99]
	s_waitcnt lgkmcnt(0)
	v_add_f32_e32 v34, v34, v96
	v_add_f32_e32 v35, v35, v97
	s_branch .LBB0_451

; __device__ __forceinline__ void partialSM(f32x16& p0, f32x16& p1, float& m_reg, float& mn, float& alpha) {
;   constexpr float C = SCALE * 1.4426950408889634f;
;   float pmax = fmaxf(p0[0], p1[0]);
; #pragma unroll
;   for (int r = 1; r < 16; ++r) pmax = __builtin_fmaxf(__builtin_fmaxf(pmax, p0[r]), p1[r]);
;   { auto rr = __builtin_amdgcn_permlane32_swap(__float_as_uint(pmax), __float_as_uint(pmax), false, false);
;     pmax = fmaxf(__uint_as_float(rr[0]), __uint_as_float(rr[1])); }
;   if (__builtin_expect(__all(pmax - m_reg <= THR / SCALE), 1)) { mn = m_reg; alpha = 1.f; }
;   else { mn = fmaxf(m_reg, pmax); alpha = __builtin_amdgcn_exp2f((m_reg - mn) * C); m_reg = mn; }
;   float mnC = -mn * C;
; #pragma unroll
;   for (int r = 0; r < 16; ++r) p0[r] = fmaf(p0[r], C, mnC);
; #pragma unroll
;   for (int r = 0; r < 16; ++r) p1[r] = fmaf(p1[r], C, mnC);
; #pragma unroll
;   for (int r = 0; r < 16; ++r) p0[r] = __builtin_amdgcn_exp2f(p0[r]);
; }
; __device__ __forceinline__ void finishSM(f32x16& p0, f32x16& p1, float alpha, float& l_reg, bf16x8& pa0, bf16x8& pa1, bf16x8& pa2, bf16x8& pa3) {
; #pragma unroll
;   for (int r = 0; r < 16; ++r) p1[r] = __builtin_amdgcn_exp2f(p1[r]);
;   float ps = 0;
; #pragma unroll
;   for (int r = 0; r < 16; ++r) ps += p0[r];
; #pragma unroll
;   for (int r = 0; r < 16; ++r) ps += p1[r];
;   { auto rr = __builtin_amdgcn_permlane32_swap(__float_as_uint(ps), __float_as_uint(ps), false, false);
;     ps = __uint_as_float(rr[0]) + __uint_as_float(rr[1]); }
;   l_reg = l_reg * alpha + ps;
;     ...
;   PK4(p0, 0, pa0); PK4(p0, 8, pa1); PK4(p1, 0, pa2); PK4(p1, 8, pa3);
; __device__ __forceinline__ void attn_unit2(const bf16* __restrict__ Qb, const bf16* __restrict__ Kh, const bf16* __restrict__ Vh, bf16* __restrict__ Ob,
;                                            int NT, int lim, int qrow0, const float* lut, char* lds, float* scr) {
;     ...
;         partialSM(p0, p1, m_reg, mn, al);
;         finishSM(p0, p1, al, l_reg, pa0, pa1, pa2, pa3);
;         __builtin_amdgcn_s_setprio(0);
;         char* ps = P_lds + (j & 1) * 16384 + lane * 16;
;         *(bf16x8*)(ps) = pa0; *(bf16x8*)(ps + 1024) = pa1; *(bf16x8*)(ps + 2048) = pa2; *(bf16x8*)(ps + 3072) = pa3;
;         if (hi == 0) alpha_l[(j & 1) * 128 + r32] = al;
;       }
;       __syncthreads();
.LBB0_451:
	s_nop 8
	v_max_f32_e32 v81, v20, v20
	v_max_f32_e32 v82, v4, v4
	v_max_f32_e32 v81, v82, v81
	v_max3_f32 v81, v81, v5, v21
	v_max3_f32 v81, v81, v6, v22
	v_max3_f32 v81, v81, v7, v23
	v_max3_f32 v81, v81, v8, v24
	v_max3_f32 v81, v81, v9, v25
	v_max3_f32 v81, v81, v10, v26
	v_max3_f32 v81, v81, v11, v27
	s_nop 0
	v_max3_f32 v81, v81, v12, v28
	v_max3_f32 v81, v81, v13, v29
	v_max3_f32 v81, v81, v14, v30
	v_max3_f32 v81, v81, v15, v31
	v_max3_f32 v81, v81, v16, v32
	v_max3_f32 v81, v81, v17, v33
	v_max3_f32 v81, v81, v18, v34
	v_max3_f32 v81, v81, v19, v35
	v_mov_b32_e32 v82, v81
	s_nop 1
	v_permlane32_swap_b32_e32 v81, v82
	v_max_f32_e32 v82, v82, v82
	v_max_f32_e32 v81, v81, v81
	v_max_f32_e32 v81, v81, v82
	v_sub_f32_e32 v82, v81, v79
	v_cmp_ge_f32_e64 s[38:39], s31, v82
	v_max_f32_e32 v83, v79, v79
	s_cmp_eq_u64 s[38:39], exec
	v_max_f32_e32 v83, v83, v81
	s_cselect_b64 s[38:39], -1, 0
	v_sub_f32_e32 v81, v79, v83
	v_cndmask_b32_e64 v79, v83, v79, s[38:39]
	v_mul_f32_e32 v82, 0xbe0293ee, v79
	v_fmamk_f32 v4, v4, 0x3e0293ee, v82
	v_fmamk_f32 v5, v5, 0x3e0293ee, v82
	v_fmamk_f32 v6, v6, 0x3e0293ee, v82
	v_fmamk_f32 v7, v7, 0x3e0293ee, v82
	v_fmamk_f32 v8, v8, 0x3e0293ee, v82
	v_fmamk_f32 v9, v9, 0x3e0293ee, v82
	v_fmamk_f32 v10, v10, 0x3e0293ee, v82
	v_fmamk_f32 v11, v11, 0x3e0293ee, v82
	v_fmamk_f32 v12, v12, 0x3e0293ee, v82
	v_fmamk_f32 v13, v13, 0x3e0293ee, v82
	v_fmamk_f32 v14, v14, 0x3e0293ee, v82
	v_fmamk_f32 v15, v15, 0x3e0293ee, v82
	v_fmamk_f32 v16, v16, 0x3e0293ee, v82
	v_fmamk_f32 v17, v17, 0x3e0293ee, v82
	v_fmamk_f32 v18, v18, 0x3e0293ee, v82
	v_fmamk_f32 v19, v19, 0x3e0293ee, v82
	v_fmamk_f32 v20, v20, 0x3e0293ee, v82
	v_fmamk_f32 v21, v21, 0x3e0293ee, v82
	v_fmamk_f32 v22, v22, 0x3e0293ee, v82
	v_fmamk_f32 v23, v23, 0x3e0293ee, v82
	v_fmamk_f32 v24, v24, 0x3e0293ee, v82
	v_fmamk_f32 v25, v25, 0x3e0293ee, v82
	v_fmamk_f32 v26, v26, 0x3e0293ee, v82
	v_fmamk_f32 v27, v27, 0x3e0293ee, v82
	v_fmamk_f32 v28, v28, 0x3e0293ee, v82
	v_fmamk_f32 v29, v29, 0x3e0293ee, v82
	v_fmamk_f32 v30, v30, 0x3e0293ee, v82
	v_fmamk_f32 v31, v31, 0x3e0293ee, v82
	v_fmamk_f32 v32, v32, 0x3e0293ee, v82
	v_fmamk_f32 v33, v33, 0x3e0293ee, v82
	v_fmamk_f32 v34, v34, 0x3e0293ee, v82
	v_fmac_f32_e32 v82, 0x3e0293ee, v35
	v_exp_f32_e32 v35, v4
	v_exp_f32_e32 v83, v5
	v_exp_f32_e32 v84, v6
	v_exp_f32_e32 v7, v7
	v_exp_f32_e32 v8, v8
	v_add_f32_e32 v4, 0, v35
	v_exp_f32_e32 v9, v9
	v_add_f32_e32 v4, v83, v4
	v_exp_f32_e32 v10, v10
	v_add_f32_e32 v4, v84, v4
	v_exp_f32_e32 v11, v11
	v_add_f32_e32 v4, v7, v4
	v_exp_f32_e32 v12, v12
	v_add_f32_e32 v4, v8, v4
	v_exp_f32_e32 v13, v13
	v_add_f32_e32 v4, v9, v4
	v_exp_f32_e32 v14, v14
	v_add_f32_e32 v4, v10, v4
	v_exp_f32_e32 v15, v15
	v_add_f32_e32 v4, v11, v4
	v_exp_f32_e32 v16, v16
	v_add_f32_e32 v4, v12, v4
	v_exp_f32_e32 v17, v17
	v_add_f32_e32 v4, v13, v4
	v_exp_f32_e32 v18, v18
	v_add_f32_e32 v4, v14, v4
	v_exp_f32_e32 v19, v19
	v_add_f32_e32 v4, v15, v4
	v_exp_f32_e32 v20, v20
	v_add_f32_e32 v4, v16, v4
	v_exp_f32_e32 v21, v21
	v_add_f32_e32 v4, v17, v4
	v_exp_f32_e32 v22, v22
	v_add_f32_e32 v4, v18, v4
	v_exp_f32_e32 v23, v23
	v_add_f32_e32 v4, v19, v4
	v_exp_f32_e32 v24, v24
	v_add_f32_e32 v4, v20, v4
	v_exp_f32_e32 v25, v25
	v_add_f32_e32 v4, v21, v4
	v_exp_f32_e32 v26, v26
	v_add_f32_e32 v4, v22, v4
	v_exp_f32_e32 v27, v27
	v_add_f32_e32 v4, v23, v4
	v_exp_f32_e32 v28, v28
	v_add_f32_e32 v4, v24, v4
	v_exp_f32_e32 v29, v29
	v_add_f32_e32 v4, v25, v4
	v_exp_f32_e32 v30, v30
	v_add_f32_e32 v4, v26, v4
	v_exp_f32_e32 v31, v31
	v_add_f32_e32 v4, v27, v4
	v_exp_f32_e32 v32, v32
	v_add_f32_e32 v4, v28, v4
	v_exp_f32_e32 v33, v33
	v_add_f32_e32 v4, v29, v4
	v_exp_f32_e32 v34, v34
	v_add_f32_e32 v4, v30, v4
	v_exp_f32_e32 v82, v82
	v_add_f32_e32 v4, v31, v4
	v_mul_f32_e32 v81, 0x3e0293ee, v81
	v_add_f32_e32 v4, v32, v4
	v_exp_f32_e32 v81, v81
	v_add_f32_e32 v4, v33, v4
	v_add_f32_e32 v4, v34, v4
	v_add_f32_e32 v4, v82, v4
	v_mov_b32_e32 v5, v4
	v_cndmask_b32_e64 v81, v81, 1.0, s[38:39]
	s_nop 0
	v_permlane32_swap_b32_e32 v4, v5
	v_cvt_pk_bf16_f32 v6, v35, v83
	v_cvt_pk_bf16_f32 v7, v84, v7
	v_cvt_pk_bf16_f32 v8, v8, v9
	v_cvt_pk_bf16_f32 v9, v10, v11
	v_cvt_pk_bf16_f32 v10, v12, v13
	v_cvt_pk_bf16_f32 v11, v14, v15
	v_cvt_pk_bf16_f32 v12, v16, v17
	v_cvt_pk_bf16_f32 v13, v18, v19
	v_cvt_pk_bf16_f32 v14, v20, v21
	v_cvt_pk_bf16_f32 v15, v22, v23
	v_cvt_pk_bf16_f32 v16, v24, v25
	v_cvt_pk_bf16_f32 v17, v26, v27
	v_cvt_pk_bf16_f32 v18, v28, v29
	v_cvt_pk_bf16_f32 v19, v30, v31
	v_cvt_pk_bf16_f32 v20, v32, v33
	v_cvt_pk_bf16_f32 v21, v34, v82
	s_nop 0
	v_permlane32_swap_b32_e32 v6, v8
	v_permlane32_swap_b32_e32 v7, v9
	v_permlane32_swap_b32_e32 v10, v12
	v_permlane32_swap_b32_e32 v11, v13
	v_permlane32_swap_b32_e32 v14, v16
	v_permlane32_swap_b32_e32 v15, v17
	v_permlane32_swap_b32_e32 v18, v20
	v_permlane32_swap_b32_e32 v19, v21
	s_setprio 0
	v_add_u32_e32 v22, s15, v2
	ds_write_b128 v22, v[6:9]
	ds_write_b128 v22, v[10:13] offset:1024
	ds_write_b128 v22, v[14:17] offset:2048
	ds_write_b128 v22, v[18:21] offset:3072
	s_and_saveexec_b64 s[36:37], vcc
	v_lshl_add_u32 v6, s14, 9, v68
	ds_write_b32 v6, v81
	s_or_b64 exec, exec, s[36:37]
	v_add_f32_e32 v4, v4, v5
	s_add_i32 s10, s10, 1
	s_addk_i32 s8, 0x100
	s_add_i32 s9, s9, 64
	v_fmac_f32_e32 v4, v80, v81
	s_cmp_eq_u32 s7, s8
	s_waitcnt lgkmcnt(0)
	s_barrier
	s_cbranch_scc1 .LBB0_455
	v_mov_b32_e32 v80, v4
	s_branch .LBB0_447
